# vAA + sc1 write-through on P2 attention-output stores and EpiGate0 stores
# baseline (speedup 1.0000x reference)
.LBB0_470:
	v_ashrrev_i32_e32 v3, 3, v2
	s_add_i32 s1, 0, 0x18000
	v_add_u32_e32 v8, 0x100, v3
	v_add_u32_e32 v12, 0x200, v3
	v_lshl_add_u32 v4, v3, 2, s1
	v_lshl_add_u32 v5, v8, 2, s1
	v_lshl_add_u32 v6, v12, 2, s1
	ds_read_b32 v4, v4
	ds_read_b32 v5, v5
	ds_read_b32 v6, v6
	v_lshl_add_u32 v12, v12, 7, v198
	ds_read_b128 v[12:15], v12
	v_lshl_add_u32 v8, v8, 7, v198
	s_movk_i32 s1, 0x5ff
	s_waitcnt lgkmcnt(1)
	v_max3_f32 v7, v4, v5, v6
	v_sub_f32_e32 v4, v4, v7
	v_exp_f32_e32 v17, v4
	v_sub_f32_e32 v4, v5, v7
	v_exp_f32_e32 v4, v4
	v_sub_f32_e32 v5, v6, v7
	v_exp_f32_e32 v16, v5
	v_add_f32_e32 v5, v17, v4
	v_add_f32_e32 v5, v16, v5
	v_div_scale_f32 v6, s[4:5], v5, v5, 1.0
	v_rcp_f32_e32 v7, v6
	s_nop 0
	v_fma_f32 v9, -v6, v7, 1.0
	v_fmac_f32_e32 v7, v9, v7
	v_div_scale_f32 v9, vcc, 1.0, v5, 1.0
	v_mul_f32_e32 v10, v9, v7
	v_fma_f32 v11, -v6, v10, v9
	v_fmac_f32_e32 v10, v11, v7
	v_fma_f32 v6, -v6, v10, v9
	v_div_fmas_f32 v6, v6, v7, v10
	v_div_fixup_f32 v18, v6, v5, 1.0
	v_mul_f32_e32 v19, v4, v18
	v_lshl_add_u32 v4, v3, 7, v198
	ds_read_b128 v[4:7], v4
	ds_read_b128 v[8:11], v8
	v_cmp_lt_i32_e32 vcc, s1, v2
	s_or_b64 s[36:37], vcc, s[36:37]
	s_waitcnt lgkmcnt(0)
	v_lshlrev_b32_e32 v20, 16, v8
	v_and_b32_e32 v21, 0xffff0000, v8
	v_lshlrev_b32_e32 v22, 16, v9
	v_and_b32_e32 v23, 0xffff0000, v9
	v_pk_mul_f32 v[8:9], v[16:17], v[18:19] op_sel_hi:[1,0]
	v_lshlrev_b32_e32 v17, 16, v4
	v_lshlrev_b32_e32 v16, 16, v12
	v_pk_mul_f32 v[16:17], v[8:9], v[16:17]
	v_lshlrev_b32_e32 v24, 16, v10
	v_fma_f32 v17, v19, v20, v17
	v_add_f32_e32 v18, v16, v17
	v_and_b32_e32 v17, 0xffff0000, v4
	v_and_b32_e32 v16, 0xffff0000, v12
	v_pk_mul_f32 v[16:17], v[8:9], v[16:17]
	v_and_b32_e32 v25, 0xffff0000, v10
	v_fma_f32 v4, v19, v21, v17
	v_add_f32_e32 v12, v16, v4
	v_lshlrev_b32_e32 v17, 16, v5
	v_lshlrev_b32_e32 v16, 16, v13
	v_pk_mul_f32 v[16:17], v[8:9], v[16:17]
	v_and_b32_e32 v5, 0xffff0000, v5
	v_fma_f32 v4, v19, v22, v17
	v_add_f32_e32 v16, v16, v4
	v_and_b32_e32 v4, 0xffff0000, v13
	v_pk_mul_f32 v[4:5], v[8:9], v[4:5]
	v_lshlrev_b32_e32 v26, 16, v11
	v_fma_f32 v5, v19, v23, v5
	v_add_f32_e32 v13, v4, v5
	v_lshlrev_b32_e32 v5, 16, v6
	v_lshlrev_b32_e32 v4, 16, v14
	v_pk_mul_f32 v[4:5], v[8:9], v[4:5]
	v_and_b32_e32 v27, 0xffff0000, v11
	v_fma_f32 v5, v19, v24, v5
	v_add_f32_e32 v17, v4, v5
	v_and_b32_e32 v5, 0xffff0000, v6
	v_and_b32_e32 v4, 0xffff0000, v14
	v_pk_mul_f32 v[4:5], v[8:9], v[4:5]
	v_lshlrev_b32_e32 v11, 16, v7
	v_lshlrev_b32_e32 v10, 16, v15
	v_fma_f32 v5, v19, v25, v5
	v_add_f32_e32 v6, v4, v5
	v_pk_mul_f32 v[4:5], v[8:9], v[10:11]
	s_nop 0
	v_fma_f32 v5, v19, v26, v5
	v_add_f32_e32 v10, v4, v5
	v_and_b32_e32 v5, 0xffff0000, v7
	v_and_b32_e32 v4, 0xffff0000, v15
	v_pk_mul_f32 v[4:5], v[8:9], v[4:5]
	v_add_u32_e32 v8, s0, v3
	v_ashrrev_i32_e32 v9, 31, v8
	v_fma_f32 v5, v19, v27, v5
	v_lshlrev_b64 v[8:9], 9, v[8:9]
	v_add_u32_e32 v3, 0x200, v2
	v_add_f32_e32 v7, v4, v5
	v_lshl_add_u64 v[8:9], v[0:1], 0, v[8:9]
	v_mov_b32_e32 v2, v3
	v_cvt_pk_bf16_f32 v4, v18, v12
	v_cvt_pk_bf16_f32 v5, v16, v13
	v_cvt_pk_bf16_f32 v6, v17, v6
	v_cvt_pk_bf16_f32 v7, v10, v7
	global_store_dwordx4 v[8:9], v[4:7], off sc1
	s_andn2_b64 exec, exec, s[36:37]
	s_cbranch_execnz .LBB0_470
	s_branch .LBB0_365

.LBB0_473:
	v_lshl_or_b32 v0, s27, 11, v191
	v_ashrrev_i32_e32 v1, 31, v0
	v_lshlrev_b64 v[0:1], 9, v[0:1]
	v_lshl_add_u64 v[0:1], v[158:159], 0, v[0:1]
	s_lshl_b32 s92, s28, 1
	v_lshl_add_u64 v[0:1], v[0:1], 0, s[92:93]
	v_cvt_pk_bf16_f32 v2, v132, v133
	v_cvt_pk_bf16_f32 v3, v134, v135
	global_store_dwordx2 v[0:1], v[2:3], off sc1
	v_cvt_pk_bf16_f32 v2, v128, v129
	v_cvt_pk_bf16_f32 v3, v130, v131
	global_store_dwordx2 v[0:1], v[2:3], off offset:32 sc1
	v_cvt_pk_bf16_f32 v2, v124, v125
	v_cvt_pk_bf16_f32 v3, v126, v127
	global_store_dwordx2 v[0:1], v[2:3], off offset:64 sc1
	v_cvt_pk_bf16_f32 v2, v120, v121
	v_cvt_pk_bf16_f32 v3, v122, v123
	global_store_dwordx2 v[0:1], v[2:3], off offset:96 sc1
	v_cvt_pk_bf16_f32 v2, v116, v117
	v_cvt_pk_bf16_f32 v3, v118, v119
	s_and_b64 vcc, exec, s[0:1]
	global_store_dwordx2 v[0:1], v[2:3], off offset:128 sc1
	v_cvt_pk_bf16_f32 v2, v112, v113
	v_cvt_pk_bf16_f32 v3, v114, v115
	s_add_i32 s20, s20, s68
	s_add_i32 s12, s12, s68
	global_store_dwordx2 v[0:1], v[2:3], off offset:160 sc1
	v_cvt_pk_bf16_f32 v2, v108, v109
	v_cvt_pk_bf16_f32 v3, v110, v111
	s_cmpk_gt_i32 s20, 0x7ff
	global_store_dwordx2 v[0:1], v[2:3], off offset:192 sc1
	v_cvt_pk_bf16_f32 v2, v64, v65
	v_cvt_pk_bf16_f32 v3, v66, v67
	global_store_dwordx2 v[0:1], v[2:3], off offset:224 sc1
	s_cbranch_scc1 .LBB0_478

.LBB0_573:
	s_lshl_b32 s0, s71, 8
	v_mbcnt_lo_u32_b32 v116, -1, 0
	v_mbcnt_hi_u32_b32 v116, -1, v116
	s_add_i32 s0, s0, s66
	v_and_or_b32 v164, v116, 15, s0
	s_lshl_b32 s0, s70, 8
	v_ashrrev_i32_e32 v116, 1, v116
	s_or_b32 s0, s0, s67
	v_and_b32_e32 v116, -8, v116
	v_add_u32_e32 v116, s0, v116
	v_ashrrev_i32_e32 v117, 31, v116
	v_mov_b64_e32 v[166:167], s[36:37]
	v_mad_i64_i32 v[118:119], s[0:1], v164, s15, v[166:167]
	v_lshlrev_b64 v[162:163], 1, v[116:117]
	v_lshl_add_u64 v[116:117], v[118:119], 0, v[162:163]
	v_lshl_add_u64 v[118:119], v[116:117], 0, s[84:85]
	v_add_co_u32_e32 v116, vcc, s19, v116
	v_or_b32_e32 v172, 16, v164
	s_nop 0
	v_addc_co_u32_e32 v117, vcc, 0, v117, vcc
	global_load_dwordx4 v[178:181], v[116:117], off offset:2048
	global_load_dwordx4 v[144:147], v[118:119], off offset:256
	v_mad_i64_i32 v[116:117], s[0:1], v172, s15, v[166:167]
	v_lshl_add_u64 v[116:117], v[116:117], 0, v[162:163]
	v_lshl_add_u64 v[118:119], v[116:117], 0, s[84:85]
	v_add_co_u32_e32 v116, vcc, s19, v116
	v_or_b32_e32 v170, 32, v164
	s_nop 0
	v_addc_co_u32_e32 v117, vcc, 0, v117, vcc
	global_load_dwordx4 v[140:143], v[116:117], off offset:2048
	global_load_dwordx4 v[136:139], v[118:119], off offset:256
	v_mad_i64_i32 v[116:117], s[0:1], v170, s15, v[166:167]
	v_lshl_add_u64 v[116:117], v[116:117], 0, v[162:163]
	v_lshl_add_u64 v[118:119], v[116:117], 0, s[84:85]
	v_add_co_u32_e32 v116, vcc, s19, v116
	v_or_b32_e32 v168, 48, v164
	s_nop 0
	v_addc_co_u32_e32 v117, vcc, 0, v117, vcc
	global_load_dwordx4 v[128:131], v[116:117], off offset:2048
	s_nop 0
	global_load_dwordx4 v[116:119], v[118:119], off offset:256
	v_mad_i64_i32 v[120:121], s[0:1], v168, s15, v[166:167]
	v_lshl_add_u64 v[120:121], v[120:121], 0, v[162:163]
	v_lshl_add_u64 v[122:123], v[120:121], 0, s[84:85]
	v_add_co_u32_e32 v120, vcc, s19, v120
	v_ashrrev_i32_e32 v165, 31, v164
	s_nop 0
	v_addc_co_u32_e32 v121, vcc, 0, v121, vcc
	global_load_dwordx4 v[132:135], v[120:121], off offset:2048
	s_nop 0
	global_load_dwordx4 v[120:123], v[122:123], off offset:256
	v_lshlrev_b64 v[182:183], 11, v[164:165]
	v_ashrrev_i32_e32 v173, 31, v172
	v_ashrrev_i32_e32 v171, 31, v170
	v_ashrrev_i32_e32 v169, 31, v168
	v_mov_b64_e32 v[242:243], v[184:185]
	v_mov_b64_e32 v[184:185], 0xff
	s_waitcnt vmcnt(0)
	v_lshlrev_b32_e32 v165, 16, v178
	v_mul_f32_e32 v152, v152, v165
	v_and_b32_e32 v165, 0xffff0000, v178
	v_mul_f32_e32 v153, v153, v165
	v_lshlrev_b32_e32 v165, 16, v179
	v_mul_f32_e32 v154, v154, v165
	v_and_b32_e32 v165, 0xffff0000, v179
	v_mul_f32_e32 v155, v155, v165
	v_lshlrev_b32_e32 v165, 16, v180
	v_mul_f32_e32 v165, v148, v165
	v_and_b32_e32 v148, 0xffff0000, v180
	v_mul_f32_e32 v178, v149, v148
	v_lshlrev_b32_e32 v148, 16, v181
	v_mul_f32_e32 v179, v150, v148
	v_and_b32_e32 v148, 0xffff0000, v181
	v_mul_f32_e32 v151, v151, v148
	v_cvt_pk_bf16_f32 v148, v152, v153
	v_lshl_add_u64 v[152:153], s[30:31], 0, v[182:183]
	v_lshl_add_u64 v[152:153], v[152:153], 0, v[162:163]
	v_cvt_pk_bf16_f32 v149, v154, v155
	v_cvt_pk_bf16_f32 v150, v165, v178
	v_cvt_pk_bf16_f32 v151, v179, v151
	global_store_dwordx4 v[152:153], v[148:151], off sc1
	s_nop 1
	v_lshlrev_b32_e32 v148, 16, v144
	v_and_b32_e32 v144, 0xffff0000, v144
	v_mul_f32_e32 v125, v125, v144
	v_lshlrev_b32_e32 v144, 16, v145
	v_mul_f32_e32 v126, v126, v144
	v_and_b32_e32 v144, 0xffff0000, v145
	v_mul_f32_e32 v127, v127, v144
	v_lshlrev_b32_e32 v144, 16, v146
	v_mul_f32_e32 v144, v112, v144
	v_and_b32_e32 v112, 0xffff0000, v146
	v_mul_f32_e32 v145, v113, v112
	v_lshlrev_b32_e32 v112, 16, v147
	v_mul_f32_e32 v146, v114, v112
	v_and_b32_e32 v112, 0xffff0000, v147
	v_mul_f32_e32 v124, v124, v148
	v_mul_f32_e32 v115, v115, v112
	v_cvt_pk_bf16_f32 v112, v124, v125
	v_cvt_pk_bf16_f32 v113, v126, v127
	v_cvt_pk_bf16_f32 v114, v144, v145
	v_cvt_pk_bf16_f32 v115, v146, v115
	global_store_dwordx4 v[152:153], v[112:115], off offset:256 sc1
	s_nop 1
	v_lshlrev_b32_e32 v114, 16, v140
	v_mul_f32_e32 v108, v108, v114
	v_and_b32_e32 v114, 0xffff0000, v140
	v_mul_f32_e32 v109, v109, v114
	v_lshlrev_b32_e32 v114, 16, v141
	v_mul_f32_e32 v110, v110, v114
	v_and_b32_e32 v114, 0xffff0000, v141
	v_mul_f32_e32 v111, v111, v114
	v_lshlrev_b32_e32 v114, 16, v142
	v_mul_f32_e32 v114, v104, v114
	v_and_b32_e32 v104, 0xffff0000, v142
	v_mul_f32_e32 v115, v105, v104
	v_lshlrev_b32_e32 v104, 16, v143
	v_lshlrev_b64 v[112:113], 11, v[172:173]
	v_mul_f32_e32 v124, v106, v104
	v_and_b32_e32 v104, 0xffff0000, v143
	v_mul_f32_e32 v107, v107, v104
	v_cvt_pk_bf16_f32 v104, v108, v109
	v_lshl_add_u64 v[108:109], s[30:31], 0, v[112:113]
	v_lshl_add_u64 v[108:109], v[108:109], 0, v[162:163]
	v_cvt_pk_bf16_f32 v105, v110, v111
	v_cvt_pk_bf16_f32 v106, v114, v115
	v_cvt_pk_bf16_f32 v107, v124, v107
	global_store_dwordx4 v[108:109], v[104:107], off sc1
	s_nop 1
	v_lshlrev_b32_e32 v104, 16, v136
	v_mul_f32_e32 v100, v100, v104
	v_and_b32_e32 v104, 0xffff0000, v136
	v_mul_f32_e32 v101, v101, v104
	v_lshlrev_b32_e32 v104, 16, v137
	v_mul_f32_e32 v102, v102, v104
	v_and_b32_e32 v104, 0xffff0000, v137
	v_mul_f32_e32 v103, v103, v104
	v_lshlrev_b32_e32 v104, 16, v138
	v_mul_f32_e32 v104, v96, v104
	v_and_b32_e32 v96, 0xffff0000, v138
	v_mul_f32_e32 v105, v97, v96
	v_lshlrev_b32_e32 v96, 16, v139
	v_mul_f32_e32 v106, v98, v96
	v_and_b32_e32 v96, 0xffff0000, v139
	v_mul_f32_e32 v99, v99, v96
	v_cvt_pk_bf16_f32 v96, v100, v101
	v_cvt_pk_bf16_f32 v97, v102, v103
	v_cvt_pk_bf16_f32 v98, v104, v105
	v_cvt_pk_bf16_f32 v99, v106, v99
	global_store_dwordx4 v[108:109], v[96:99], off offset:256 sc1
	v_add_u32_e32 v102, 0xb0, v164
	v_ashrrev_i32_e32 v103, 31, v102
	v_lshlrev_b32_e32 v98, 16, v128
	v_mul_f32_e32 v92, v92, v98
	v_and_b32_e32 v98, 0xffff0000, v128
	v_mul_f32_e32 v93, v93, v98
	v_lshlrev_b32_e32 v98, 16, v129
	v_mul_f32_e32 v94, v94, v98
	v_and_b32_e32 v98, 0xffff0000, v129
	v_mul_f32_e32 v95, v95, v98
	v_lshlrev_b32_e32 v98, 16, v130
	v_mul_f32_e32 v98, v88, v98
	v_and_b32_e32 v88, 0xffff0000, v130
	v_mul_f32_e32 v99, v89, v88
	v_lshlrev_b32_e32 v88, 16, v131
	v_lshlrev_b64 v[96:97], 11, v[170:171]
	v_mul_f32_e32 v100, v90, v88
	v_and_b32_e32 v88, 0xffff0000, v131
	v_mul_f32_e32 v91, v91, v88
	v_cvt_pk_bf16_f32 v88, v92, v93
	v_lshl_add_u64 v[92:93], s[30:31], 0, v[96:97]
	v_lshl_add_u64 v[92:93], v[92:93], 0, v[162:163]
	v_cvt_pk_bf16_f32 v89, v94, v95
	v_cvt_pk_bf16_f32 v90, v98, v99
	v_cvt_pk_bf16_f32 v91, v100, v91
	global_store_dwordx4 v[92:93], v[88:91], off sc1
	v_add_u32_e32 v96, 0x80, v164
	v_add_u32_e32 v98, 0x90, v164
	v_lshlrev_b32_e32 v88, 16, v116
	v_mul_f32_e32 v84, v84, v88
	v_and_b32_e32 v88, 0xffff0000, v116
	v_mul_f32_e32 v85, v85, v88
	v_lshlrev_b32_e32 v88, 16, v117
	v_mul_f32_e32 v86, v86, v88
	v_and_b32_e32 v88, 0xffff0000, v117
	v_mul_f32_e32 v87, v87, v88
	v_lshlrev_b32_e32 v88, 16, v118
	v_mul_f32_e32 v88, v80, v88
	v_and_b32_e32 v80, 0xffff0000, v118
	v_mul_f32_e32 v89, v81, v80
	v_lshlrev_b32_e32 v80, 16, v119
	v_mul_f32_e32 v90, v82, v80
	v_and_b32_e32 v80, 0xffff0000, v119
	v_mul_f32_e32 v83, v83, v80
	v_cvt_pk_bf16_f32 v80, v84, v85
	v_cvt_pk_bf16_f32 v81, v86, v87
	v_cvt_pk_bf16_f32 v82, v88, v89
	v_cvt_pk_bf16_f32 v83, v90, v83
	global_store_dwordx4 v[92:93], v[80:83], off offset:256 sc1
	v_add_u32_e32 v100, 0xa0, v164
	v_mad_i64_i32 v[88:89], s[0:1], v102, s15, v[166:167]
	v_lshlrev_b32_e32 v82, 16, v132
	v_mul_f32_e32 v76, v76, v82
	v_and_b32_e32 v82, 0xffff0000, v132
	v_mul_f32_e32 v77, v77, v82
	v_lshlrev_b32_e32 v82, 16, v133
	v_mul_f32_e32 v78, v78, v82
	v_and_b32_e32 v82, 0xffff0000, v133
	v_mul_f32_e32 v79, v79, v82
	v_lshlrev_b32_e32 v82, 16, v134
	v_mul_f32_e32 v82, v72, v82
	v_and_b32_e32 v72, 0xffff0000, v134
	v_mul_f32_e32 v83, v73, v72
	v_lshlrev_b32_e32 v72, 16, v135
	v_lshlrev_b64 v[80:81], 11, v[168:169]
	v_mul_f32_e32 v84, v74, v72
	v_and_b32_e32 v72, 0xffff0000, v135
	v_mul_f32_e32 v75, v75, v72
	v_cvt_pk_bf16_f32 v72, v76, v77
	v_lshl_add_u64 v[76:77], s[30:31], 0, v[80:81]
	v_lshl_add_u64 v[76:77], v[76:77], 0, v[162:163]
	v_cvt_pk_bf16_f32 v73, v78, v79
	v_cvt_pk_bf16_f32 v74, v82, v83
	v_cvt_pk_bf16_f32 v75, v84, v75
	global_store_dwordx4 v[76:77], v[72:75], off sc1
	v_mad_i64_i32 v[80:81], s[0:1], v100, s15, v[166:167]
	s_nop 0
	v_lshlrev_b32_e32 v72, 16, v120
	v_mul_f32_e32 v68, v68, v72
	v_and_b32_e32 v72, 0xffff0000, v120
	v_mul_f32_e32 v69, v69, v72
	v_lshlrev_b32_e32 v72, 16, v121
	v_mul_f32_e32 v70, v70, v72
	v_and_b32_e32 v72, 0xffff0000, v121
	v_mul_f32_e32 v71, v71, v72
	v_lshlrev_b32_e32 v72, 16, v122
	v_mul_f32_e32 v72, v64, v72
	v_and_b32_e32 v64, 0xffff0000, v122
	v_mul_f32_e32 v73, v65, v64
	v_lshlrev_b32_e32 v64, 16, v123
	v_mul_f32_e32 v74, v66, v64
	v_and_b32_e32 v64, 0xffff0000, v123
	v_mul_f32_e32 v67, v67, v64
	v_cvt_pk_bf16_f32 v64, v68, v69
	v_cvt_pk_bf16_f32 v65, v70, v71
	v_cvt_pk_bf16_f32 v66, v72, v73
	v_cvt_pk_bf16_f32 v67, v74, v67
	global_store_dwordx4 v[76:77], v[64:67], off offset:256 sc1
	v_mad_i64_i32 v[72:73], s[0:1], v98, s15, v[166:167]
	s_nop 0
	v_mad_i64_i32 v[64:65], s[0:1], v96, s15, v[166:167]
	v_lshl_add_u64 v[64:65], v[64:65], 0, v[162:163]
	v_lshl_add_u64 v[68:69], v[64:65], 0, s[84:85]
	v_add_co_u32_e32 v64, vcc, s19, v64
	v_lshl_add_u64 v[72:73], v[72:73], 0, v[162:163]
	s_nop 0
	v_addc_co_u32_e32 v65, vcc, 0, v65, vcc
	global_load_dwordx4 v[64:67], v[64:65], off offset:2048
	s_nop 0
	global_load_dwordx4 v[68:71], v[68:69], off offset:256
	v_lshl_add_u64 v[76:77], v[72:73], 0, s[84:85]
	v_add_co_u32_e32 v72, vcc, s19, v72
	v_lshl_add_u64 v[80:81], v[80:81], 0, v[162:163]
	s_nop 0
	v_addc_co_u32_e32 v73, vcc, 0, v73, vcc
	global_load_dwordx4 v[72:75], v[72:73], off offset:2048
	s_nop 0
	global_load_dwordx4 v[76:79], v[76:77], off offset:256
	v_lshl_add_u64 v[84:85], v[80:81], 0, s[84:85]
	v_add_co_u32_e32 v80, vcc, s19, v80
	v_lshl_add_u64 v[88:89], v[88:89], 0, v[162:163]
	s_nop 0
	v_addc_co_u32_e32 v81, vcc, 0, v81, vcc
	global_load_dwordx4 v[80:83], v[80:81], off offset:2048
	s_nop 0
	global_load_dwordx4 v[84:87], v[84:85], off offset:256
	v_lshl_add_u64 v[92:93], v[88:89], 0, s[84:85]
	v_add_co_u32_e32 v88, vcc, s19, v88
	v_ashrrev_i32_e32 v97, 31, v96
	s_nop 0
	v_addc_co_u32_e32 v89, vcc, 0, v89, vcc
	global_load_dwordx4 v[88:91], v[88:89], off offset:2048
	s_nop 0
	global_load_dwordx4 v[92:95], v[92:93], off offset:256
	v_lshlrev_b64 v[96:97], 11, v[96:97]
	v_ashrrev_i32_e32 v99, 31, v98
	v_ashrrev_i32_e32 v101, 31, v100
	s_mov_b64 s[0:1], -1
	s_andn2_b64 vcc, exec, s[40:41]
	s_waitcnt vmcnt(7)
	v_lshlrev_b32_e32 v104, 16, v64
	v_and_b32_e32 v64, 0xffff0000, v64
	v_mul_f32_e32 v61, v61, v64
	v_lshlrev_b32_e32 v64, 16, v65
	v_mul_f32_e32 v62, v62, v64
	v_and_b32_e32 v64, 0xffff0000, v65
	v_mul_f32_e32 v63, v63, v64
	v_lshlrev_b32_e32 v64, 16, v66
	v_mul_f32_e32 v64, v56, v64
	v_and_b32_e32 v56, 0xffff0000, v66
	v_mul_f32_e32 v65, v57, v56
	v_lshlrev_b32_e32 v56, 16, v67
	v_mul_f32_e32 v60, v60, v104
	v_mul_f32_e32 v66, v58, v56
	v_and_b32_e32 v56, 0xffff0000, v67
	v_mul_f32_e32 v59, v59, v56
	v_cvt_pk_bf16_f32 v56, v60, v61
	v_lshl_add_u64 v[60:61], s[30:31], 0, v[96:97]
	v_lshl_add_u64 v[60:61], v[60:61], 0, v[162:163]
	v_cvt_pk_bf16_f32 v57, v62, v63
	v_cvt_pk_bf16_f32 v58, v64, v65
	v_cvt_pk_bf16_f32 v59, v66, v59
	global_store_dwordx4 v[60:61], v[56:59], off sc1
	s_waitcnt vmcnt(7)
	s_nop 0
	v_lshlrev_b32_e32 v56, 16, v68
	v_mul_f32_e32 v52, v52, v56
	v_and_b32_e32 v56, 0xffff0000, v68
	v_mul_f32_e32 v53, v53, v56
	v_lshlrev_b32_e32 v56, 16, v69
	v_mul_f32_e32 v54, v54, v56
	v_and_b32_e32 v56, 0xffff0000, v69
	v_mul_f32_e32 v55, v55, v56
	v_lshlrev_b32_e32 v56, 16, v70
	v_mul_f32_e32 v56, v48, v56
	v_and_b32_e32 v48, 0xffff0000, v70
	v_mul_f32_e32 v57, v49, v48
	v_lshlrev_b32_e32 v48, 16, v71
	v_mul_f32_e32 v58, v50, v48
	v_and_b32_e32 v48, 0xffff0000, v71
	v_mul_f32_e32 v51, v51, v48
	v_cvt_pk_bf16_f32 v48, v52, v53
	v_cvt_pk_bf16_f32 v49, v54, v55
	v_cvt_pk_bf16_f32 v50, v56, v57
	v_cvt_pk_bf16_f32 v51, v58, v51
	global_store_dwordx4 v[60:61], v[48:51], off offset:256 sc1
	s_waitcnt vmcnt(7)
	s_nop 0
	v_lshlrev_b32_e32 v50, 16, v72
	v_mul_f32_e32 v44, v44, v50
	v_and_b32_e32 v50, 0xffff0000, v72
	v_mul_f32_e32 v45, v45, v50
	v_lshlrev_b32_e32 v50, 16, v73
	v_mul_f32_e32 v46, v46, v50
	v_and_b32_e32 v50, 0xffff0000, v73
	v_mul_f32_e32 v47, v47, v50
	v_lshlrev_b32_e32 v50, 16, v74
	v_mul_f32_e32 v50, v40, v50
	v_and_b32_e32 v40, 0xffff0000, v74
	v_mul_f32_e32 v51, v41, v40
	v_lshlrev_b32_e32 v40, 16, v75
	v_lshlrev_b64 v[48:49], 11, v[98:99]
	v_mul_f32_e32 v52, v42, v40
	v_and_b32_e32 v40, 0xffff0000, v75
	v_mul_f32_e32 v43, v43, v40
	v_cvt_pk_bf16_f32 v40, v44, v45
	v_lshl_add_u64 v[44:45], s[30:31], 0, v[48:49]
	v_lshl_add_u64 v[44:45], v[44:45], 0, v[162:163]
	v_cvt_pk_bf16_f32 v41, v46, v47
	v_cvt_pk_bf16_f32 v42, v50, v51
	v_cvt_pk_bf16_f32 v43, v52, v43
	global_store_dwordx4 v[44:45], v[40:43], off sc1
	s_waitcnt vmcnt(7)
	s_nop 0
	v_lshlrev_b32_e32 v40, 16, v76
	v_mul_f32_e32 v36, v36, v40
	v_and_b32_e32 v40, 0xffff0000, v76
	v_mul_f32_e32 v37, v37, v40
	v_lshlrev_b32_e32 v40, 16, v77
	v_mul_f32_e32 v38, v38, v40
	v_and_b32_e32 v40, 0xffff0000, v77
	v_mul_f32_e32 v39, v39, v40
	v_lshlrev_b32_e32 v40, 16, v78
	v_mul_f32_e32 v40, v32, v40
	v_and_b32_e32 v32, 0xffff0000, v78
	v_mul_f32_e32 v41, v33, v32
	v_lshlrev_b32_e32 v32, 16, v79
	v_mul_f32_e32 v42, v34, v32
	v_and_b32_e32 v32, 0xffff0000, v79
	v_mul_f32_e32 v35, v35, v32
	v_cvt_pk_bf16_f32 v32, v36, v37
	v_cvt_pk_bf16_f32 v33, v38, v39
	v_cvt_pk_bf16_f32 v34, v40, v41
	v_cvt_pk_bf16_f32 v35, v42, v35
	global_store_dwordx4 v[44:45], v[32:35], off offset:256 sc1
	s_waitcnt vmcnt(7)
	s_nop 0
	v_lshlrev_b32_e32 v34, 16, v80
	v_mul_f32_e32 v28, v28, v34
	v_and_b32_e32 v34, 0xffff0000, v80
	v_mul_f32_e32 v29, v29, v34
	v_lshlrev_b32_e32 v34, 16, v81
	v_mul_f32_e32 v30, v30, v34
	v_and_b32_e32 v34, 0xffff0000, v81
	v_mul_f32_e32 v31, v31, v34
	v_lshlrev_b32_e32 v34, 16, v82
	v_mul_f32_e32 v34, v24, v34
	v_and_b32_e32 v24, 0xffff0000, v82
	v_mul_f32_e32 v35, v25, v24
	v_lshlrev_b32_e32 v24, 16, v83
	v_lshlrev_b64 v[32:33], 11, v[100:101]
	v_mul_f32_e32 v36, v26, v24
	v_and_b32_e32 v24, 0xffff0000, v83
	v_mul_f32_e32 v27, v27, v24
	v_cvt_pk_bf16_f32 v24, v28, v29
	v_lshl_add_u64 v[28:29], s[30:31], 0, v[32:33]
	v_lshl_add_u64 v[28:29], v[28:29], 0, v[162:163]
	v_cvt_pk_bf16_f32 v25, v30, v31
	v_cvt_pk_bf16_f32 v26, v34, v35
	v_cvt_pk_bf16_f32 v27, v36, v27
	global_store_dwordx4 v[28:29], v[24:27], off sc1
	s_waitcnt vmcnt(7)
	s_nop 0
	v_lshlrev_b32_e32 v24, 16, v84
	v_mul_f32_e32 v20, v20, v24
	v_and_b32_e32 v24, 0xffff0000, v84
	v_mul_f32_e32 v21, v21, v24
	v_lshlrev_b32_e32 v24, 16, v85
	v_mul_f32_e32 v22, v22, v24
	v_and_b32_e32 v24, 0xffff0000, v85
	v_mul_f32_e32 v23, v23, v24
	v_lshlrev_b32_e32 v24, 16, v86
	v_mul_f32_e32 v24, v16, v24
	v_and_b32_e32 v16, 0xffff0000, v86
	v_mul_f32_e32 v25, v17, v16
	v_lshlrev_b32_e32 v16, 16, v87
	v_mul_f32_e32 v26, v18, v16
	v_and_b32_e32 v16, 0xffff0000, v87
	v_mul_f32_e32 v19, v19, v16
	v_cvt_pk_bf16_f32 v16, v20, v21
	v_cvt_pk_bf16_f32 v17, v22, v23
	v_cvt_pk_bf16_f32 v18, v24, v25
	v_cvt_pk_bf16_f32 v19, v26, v19
	global_store_dwordx4 v[28:29], v[16:19], off offset:256 sc1
	s_waitcnt vmcnt(7)
	s_nop 0
	v_lshlrev_b32_e32 v18, 16, v88
	v_mul_f32_e32 v12, v12, v18
	v_and_b32_e32 v18, 0xffff0000, v88
	v_mul_f32_e32 v13, v13, v18
	v_lshlrev_b32_e32 v18, 16, v89
	v_mul_f32_e32 v14, v14, v18
	v_and_b32_e32 v18, 0xffff0000, v89
	v_mul_f32_e32 v15, v15, v18
	v_lshlrev_b32_e32 v18, 16, v90
	v_mul_f32_e32 v18, v8, v18
	v_and_b32_e32 v8, 0xffff0000, v90
	v_mul_f32_e32 v19, v9, v8
	v_lshlrev_b32_e32 v8, 16, v91
	v_lshlrev_b64 v[16:17], 11, v[102:103]
	v_mul_f32_e32 v20, v10, v8
	v_and_b32_e32 v8, 0xffff0000, v91
	v_mul_f32_e32 v11, v11, v8
	v_cvt_pk_bf16_f32 v8, v12, v13
	v_lshl_add_u64 v[12:13], s[30:31], 0, v[16:17]
	v_lshl_add_u64 v[12:13], v[12:13], 0, v[162:163]
	v_cvt_pk_bf16_f32 v9, v14, v15
	v_cvt_pk_bf16_f32 v10, v18, v19
	v_cvt_pk_bf16_f32 v11, v20, v11
	global_store_dwordx4 v[12:13], v[8:11], off sc1
	s_waitcnt vmcnt(7)
	s_nop 0
	v_lshlrev_b32_e32 v8, 16, v92
	v_mul_f32_e32 v4, v4, v8
	v_and_b32_e32 v8, 0xffff0000, v92
	v_mul_f32_e32 v5, v5, v8
	v_lshlrev_b32_e32 v8, 16, v93
	v_mul_f32_e32 v6, v6, v8
	v_and_b32_e32 v8, 0xffff0000, v93
	v_mul_f32_e32 v7, v7, v8
	v_lshlrev_b32_e32 v8, 16, v94
	v_mul_f32_e32 v8, v0, v8
	v_and_b32_e32 v0, 0xffff0000, v94
	v_mul_f32_e32 v9, v1, v0
	v_lshlrev_b32_e32 v0, 16, v95
	v_mul_f32_e32 v10, v2, v0
	v_and_b32_e32 v0, 0xffff0000, v95
	v_mul_f32_e32 v3, v3, v0
	v_cvt_pk_bf16_f32 v0, v4, v5
	v_cvt_pk_bf16_f32 v1, v6, v7
	v_cvt_pk_bf16_f32 v2, v8, v9
	v_cvt_pk_bf16_f32 v3, v10, v3
	global_store_dwordx4 v[12:13], v[0:3], off offset:256 sc1
	s_cbranch_vccnz .LBB0_564
	s_andn2_b64 vcc, exec, s[28:29]
	s_cbranch_vccnz .LBB0_563
	s_barrier
	s_branch .LBB0_563
